# P5 PanelSumsq row sums: eight partial sums formed first, the two cross-lane exchanges batched (2 LDS round trips instead of 16)
# speedup vs baseline: 1.0052x; 1.0001x over previous
.LBB0_654:
	v_xor_b32_e32 v130, 16, v244
	v_cmp_lt_i32_e32 vcc, v130, v246
	v_cndmask_b32_e32 v130, v244, v130, vcc
	v_lshlrev_b32_e32 v130, 2, v130
	v_mul_f32_e32 v140, v127, v127
	v_mul_f32_e32 v150, v129, v129
	v_fmac_f32_e32 v140, v126, v126
	v_fmac_f32_e32 v150, v128, v128
	v_add_f32_e32 v140, v140, v150
	v_mul_f32_e32 v150, v123, v123
	v_mul_f32_e32 v160, v125, v125
	v_fmac_f32_e32 v150, v122, v122
	v_fmac_f32_e32 v160, v124, v124
	v_add_f32_e32 v150, v150, v160
	v_add_f32_e32 v140, v150, v140
	v_mul_f32_e32 v150, v115, v115
	v_mul_f32_e32 v160, v117, v117
	v_fmac_f32_e32 v150, v114, v114
	v_fmac_f32_e32 v160, v116, v116
	v_add_f32_e32 v150, v150, v160
	v_add_f32_e32 v140, v150, v140
	v_mul_f32_e32 v150, v111, v111
	v_mul_f32_e32 v160, v113, v113
	v_fmac_f32_e32 v150, v110, v110
	v_fmac_f32_e32 v160, v112, v112
	v_add_f32_e32 v150, v150, v160
	v_add_f32_e32 v140, v150, v140
	v_mul_f32_e32 v141, v119, v119
	v_mul_f32_e32 v151, v121, v121
	v_fmac_f32_e32 v141, v118, v118
	v_fmac_f32_e32 v151, v120, v120
	v_add_f32_e32 v141, v141, v151
	v_mul_f32_e32 v151, v107, v107
	v_mul_f32_e32 v161, v109, v109
	v_fmac_f32_e32 v151, v106, v106
	v_fmac_f32_e32 v161, v108, v108
	v_add_f32_e32 v151, v151, v161
	v_add_f32_e32 v141, v151, v141
	v_mul_f32_e32 v151, v103, v103
	v_mul_f32_e32 v161, v105, v105
	v_fmac_f32_e32 v151, v102, v102
	v_fmac_f32_e32 v161, v104, v104
	v_add_f32_e32 v151, v151, v161
	v_add_f32_e32 v141, v151, v141
	v_mul_f32_e32 v151, v91, v91
	v_mul_f32_e32 v161, v93, v93
	v_fmac_f32_e32 v151, v90, v90
	v_fmac_f32_e32 v161, v92, v92
	v_add_f32_e32 v151, v151, v161
	v_add_f32_e32 v141, v151, v141
	v_mul_f32_e32 v142, v95, v95
	v_mul_f32_e32 v152, v97, v97
	v_fmac_f32_e32 v142, v94, v94
	v_fmac_f32_e32 v152, v96, v96
	v_add_f32_e32 v142, v142, v152
	v_mul_f32_e32 v152, v83, v83
	v_mul_f32_e32 v162, v85, v85
	v_fmac_f32_e32 v152, v82, v82
	v_fmac_f32_e32 v162, v84, v84
	v_add_f32_e32 v152, v152, v162
	v_add_f32_e32 v142, v152, v142
	v_mul_f32_e32 v152, v71, v71
	v_mul_f32_e32 v162, v73, v73
	v_fmac_f32_e32 v152, v70, v70
	v_fmac_f32_e32 v162, v72, v72
	v_add_f32_e32 v152, v152, v162
	v_add_f32_e32 v142, v152, v142
	v_mul_f32_e32 v152, v59, v59
	v_mul_f32_e32 v162, v61, v61
	v_fmac_f32_e32 v152, v58, v58
	v_fmac_f32_e32 v162, v60, v60
	v_add_f32_e32 v152, v152, v162
	v_add_f32_e32 v142, v152, v142
	v_mul_f32_e32 v143, v63, v63
	v_mul_f32_e32 v153, v65, v65
	v_fmac_f32_e32 v143, v62, v62
	v_fmac_f32_e32 v153, v64, v64
	v_add_f32_e32 v143, v143, v153
	v_mul_f32_e32 v153, v67, v67
	v_mul_f32_e32 v163, v69, v69
	v_fmac_f32_e32 v153, v66, v66
	v_fmac_f32_e32 v163, v68, v68
	v_add_f32_e32 v153, v153, v163
	v_add_f32_e32 v143, v153, v143
	v_mul_f32_e32 v153, v99, v99
	v_mul_f32_e32 v163, v101, v101
	v_fmac_f32_e32 v153, v98, v98
	v_fmac_f32_e32 v163, v100, v100
	v_add_f32_e32 v153, v153, v163
	v_add_f32_e32 v143, v153, v143
	v_mul_f32_e32 v153, v87, v87
	v_mul_f32_e32 v163, v89, v89
	v_fmac_f32_e32 v153, v86, v86
	v_fmac_f32_e32 v163, v88, v88
	v_add_f32_e32 v153, v153, v163
	v_add_f32_e32 v143, v153, v143
	v_mul_f32_e32 v144, v79, v79
	v_mul_f32_e32 v154, v81, v81
	v_fmac_f32_e32 v144, v78, v78
	v_fmac_f32_e32 v154, v80, v80
	v_add_f32_e32 v144, v144, v154
	v_mul_f32_e32 v154, v75, v75
	v_mul_f32_e32 v164, v77, v77
	v_fmac_f32_e32 v154, v74, v74
	v_fmac_f32_e32 v164, v76, v76
	v_add_f32_e32 v154, v154, v164
	v_add_f32_e32 v144, v154, v144
	v_mul_f32_e32 v154, v55, v55
	v_mul_f32_e32 v164, v57, v57
	v_fmac_f32_e32 v154, v54, v54
	v_fmac_f32_e32 v164, v56, v56
	v_add_f32_e32 v154, v154, v164
	v_add_f32_e32 v144, v154, v144
	v_mul_f32_e32 v154, v47, v47
	v_mul_f32_e32 v164, v49, v49
	v_fmac_f32_e32 v154, v46, v46
	v_fmac_f32_e32 v164, v48, v48
	v_add_f32_e32 v154, v154, v164
	v_add_f32_e32 v144, v154, v144
	v_mul_f32_e32 v145, v51, v51
	v_mul_f32_e32 v155, v53, v53
	v_fmac_f32_e32 v145, v50, v50
	v_fmac_f32_e32 v155, v52, v52
	v_add_f32_e32 v145, v145, v155
	v_mul_f32_e32 v155, v43, v43
	v_mul_f32_e32 v165, v45, v45
	v_fmac_f32_e32 v155, v42, v42
	v_fmac_f32_e32 v165, v44, v44
	v_add_f32_e32 v155, v155, v165
	v_add_f32_e32 v145, v155, v145
	v_mul_f32_e32 v155, v39, v39
	v_mul_f32_e32 v165, v41, v41
	v_fmac_f32_e32 v155, v38, v38
	v_fmac_f32_e32 v165, v40, v40
	v_add_f32_e32 v155, v155, v165
	v_add_f32_e32 v145, v155, v145
	v_mul_f32_e32 v155, v31, v31
	v_mul_f32_e32 v165, v33, v33
	v_fmac_f32_e32 v155, v30, v30
	v_fmac_f32_e32 v165, v32, v32
	v_add_f32_e32 v155, v155, v165
	v_add_f32_e32 v145, v155, v145
	v_mul_f32_e32 v146, v35, v35
	v_mul_f32_e32 v156, v37, v37
	v_fmac_f32_e32 v146, v34, v34
	v_fmac_f32_e32 v156, v36, v36
	v_add_f32_e32 v146, v146, v156
	v_mul_f32_e32 v156, v27, v27
	v_mul_f32_e32 v166, v29, v29
	v_fmac_f32_e32 v156, v26, v26
	v_fmac_f32_e32 v166, v28, v28
	v_add_f32_e32 v156, v156, v166
	v_add_f32_e32 v146, v156, v146
	v_mul_f32_e32 v156, v23, v23
	v_mul_f32_e32 v166, v25, v25
	v_fmac_f32_e32 v156, v22, v22
	v_fmac_f32_e32 v166, v24, v24
	v_add_f32_e32 v156, v156, v166
	v_add_f32_e32 v146, v156, v146
	v_mul_f32_e32 v156, v15, v15
	v_mul_f32_e32 v166, v17, v17
	v_fmac_f32_e32 v156, v14, v14
	v_fmac_f32_e32 v166, v16, v16
	v_add_f32_e32 v156, v156, v166
	v_add_f32_e32 v146, v156, v146
	v_mul_f32_e32 v147, v19, v19
	v_mul_f32_e32 v157, v21, v21
	v_fmac_f32_e32 v147, v18, v18
	v_fmac_f32_e32 v157, v20, v20
	v_add_f32_e32 v147, v147, v157
	v_mul_f32_e32 v157, v11, v11
	v_mul_f32_e32 v167, v13, v13
	v_fmac_f32_e32 v157, v10, v10
	v_fmac_f32_e32 v167, v12, v12
	v_add_f32_e32 v157, v157, v167
	v_add_f32_e32 v147, v157, v147
	v_mul_f32_e32 v157, v7, v7
	v_mul_f32_e32 v167, v9, v9
	v_fmac_f32_e32 v157, v6, v6
	v_fmac_f32_e32 v167, v8, v8
	v_add_f32_e32 v157, v157, v167
	v_add_f32_e32 v147, v157, v147
	v_mul_f32_e32 v157, v3, v3
	v_mul_f32_e32 v167, v5, v5
	v_fmac_f32_e32 v157, v2, v2
	v_fmac_f32_e32 v167, v4, v4
	v_add_f32_e32 v157, v157, v167
	v_add_f32_e32 v147, v157, v147
	s_lshl_b32 s0, s37, 2
	v_cmp_gt_u32_e32 vcc, 16, v1
	s_add_i32 s2, s0, 0
	s_barrier
	ds_bpermute_b32 v170, v130, v140
	ds_bpermute_b32 v171, v130, v141
	ds_bpermute_b32 v172, v130, v142
	ds_bpermute_b32 v173, v130, v143
	ds_bpermute_b32 v174, v130, v144
	ds_bpermute_b32 v175, v130, v145
	ds_bpermute_b32 v176, v130, v146
	ds_bpermute_b32 v177, v130, v147
	s_waitcnt lgkmcnt(0)
	v_add_f32_e32 v140, v140, v170
	v_add_f32_e32 v141, v141, v171
	v_add_f32_e32 v142, v142, v172
	v_add_f32_e32 v143, v143, v173
	v_add_f32_e32 v144, v144, v174
	v_add_f32_e32 v145, v145, v175
	v_add_f32_e32 v146, v146, v176
	v_add_f32_e32 v147, v147, v177
	ds_bpermute_b32 v170, v245, v140
	ds_bpermute_b32 v171, v245, v141
	ds_bpermute_b32 v172, v245, v142
	ds_bpermute_b32 v173, v245, v143
	ds_bpermute_b32 v174, v245, v144
	ds_bpermute_b32 v175, v245, v145
	ds_bpermute_b32 v176, v245, v146
	ds_bpermute_b32 v177, v245, v147
	s_and_saveexec_b64 s[0:1], vcc
	s_cbranch_execz .LBB0_670
	s_lshl_b32 s3, s9, 10
	s_add_i32 s3, s2, s3
	v_add_u32_e32 v133, s3, v221
	s_waitcnt lgkmcnt(0)
	v_add_f32_e32 v140, v140, v170
	v_add_f32_e32 v141, v141, v171
	v_add_f32_e32 v142, v142, v172
	v_add_f32_e32 v143, v143, v173
	v_add_f32_e32 v144, v144, v174
	v_add_f32_e32 v145, v145, v175
	v_add_f32_e32 v146, v146, v176
	v_add_f32_e32 v147, v147, v177
	ds_write_b32 v133, v140
	ds_write_b32 v133, v141 offset:256
	ds_write_b32 v133, v142 offset:512
	ds_write_b32 v133, v143 offset:768
	ds_write_b32 v133, v144 offset:2048
	ds_write_b32 v133, v145 offset:2304
	ds_write_b32 v133, v146 offset:2560
	ds_write_b32 v133, v147 offset:2816
